# S5-GLU epilogue: cache the 16 bias values once per unit instead of reloading them (with a store-ack wait) before every row
# speedup vs baseline: 1.0188x; 1.0002x over previous
; #define PG8_LAS __attribute__((address_space(3)))
; __device__ __forceinline__ unsigned cvt_pk_bf16(float lo, float hi) { unsigned r; asm volatile("v_cvt_pk_bf16_f32 %0, %1, %2" : "=v"(r) : "v"(lo), "v"(hi)); return r; }
; __device__ __forceinline__ float fast_sigmoid(float x) { return __builtin_amdgcn_rcpf(1.0f + __expf(-x)); }
;     __device__ __forceinline__ void operator()(const f32x4 (&acc)[2][2][4][2], const Unit& u, int wr, int wc, int fr, int fq, PG8_LAS unsigned char* ldsb) const {
;         const int row0 = u.pm * BM + wr * 64 + fr; const int col0 = u.pn * BM + wc * 32 + 8 * fq;
; #pragma unroll
;         for (int ai = 0; ai < 2; ++ai) {
;             u32x4 zv[4][2];
; #pragma unroll
;             for (int m = 0; m < 4; ++m)
; #pragma unroll
;                 for (int bj = 0; bj < 2; ++bj) zv[m][bj] = *(const u32x4*)(Zs + ((unsigned)(row0 + ai * HALF + m * 16) * 512u + (unsigned)(col0 + bj * HALF)));
; #pragma unroll
;             for (int m = 0; m < 4; ++m) {
;                 const int row = row0 + ai * HALF + m * 16;
; #pragma unroll
;                 for (int bj = 0; bj < 2; ++bj) {
;                     const int c = col0 + bj * HALF;
;                     const u32x4 zw = zv[m][bj];
;                     float v[8];
; #pragma unroll
;                     for (int n = 0; n < 2; ++n)
; #pragma unroll
;                         for (int i = 0; i < 4; ++i) { const int e = n * 4 + i; const unsigned wd = zw[e >> 1];
;                             const float z = __uint_as_float((e & 1) ? (wd & 0xffff0000u) : (wd << 16));
;                             v[e] = z * fast_sigmoid(acc[ai][bj][m][n][i] + bias[c + e]); }
;                     u32x4 w; w.x = cvt_pk_bf16(v[0], v[1]); w.y = cvt_pk_bf16(v[2], v[3]); w.z = cvt_pk_bf16(v[4], v[5]); w.w = cvt_pk_bf16(v[6], v[7]);
;                     *(u32x4*)(O + (size_t)row * ldo + c) = w;
;                 }
;             }
.LBB0_825:
	v_lshl_add_u32 v180, s1, 8, v184
	v_lshl_or_b32 v182, s56, 8, v194
	v_lshl_add_u32 v0, v180, 9, v182
	v_lshl_add_u64 v[90:91], v[0:1], 1, s[6:7]
	global_load_dwordx4 v[158:161], v[90:91], off
	v_or_b32_e32 v90, 0x80, v0
	v_mov_b32_e32 v91, v1
	v_lshl_add_u64 v[90:91], v[90:91], 1, s[6:7]
	global_load_dwordx4 v[154:157], v[90:91], off
	v_add_u32_e32 v90, 0x2000, v0
	v_mov_b32_e32 v91, v1
	v_lshl_add_u64 v[90:91], v[90:91], 1, s[6:7]
	global_load_dwordx4 v[150:153], v[90:91], off
	v_add_u32_e32 v90, 0x2080, v0
	v_mov_b32_e32 v91, v1
	v_lshl_add_u64 v[90:91], v[90:91], 1, s[6:7]
	global_load_dwordx4 v[134:137], v[90:91], off
	v_add_u32_e32 v90, 0x4000, v0
	v_mov_b32_e32 v91, v1
	v_lshl_add_u64 v[90:91], v[90:91], 1, s[6:7]
	global_load_dwordx4 v[126:129], v[90:91], off
	v_add_u32_e32 v90, 0x4080, v0
	v_mov_b32_e32 v91, v1
	v_lshl_add_u64 v[90:91], v[90:91], 1, s[6:7]
	global_load_dwordx4 v[110:113], v[90:91], off
	v_add_u32_e32 v90, 0x6000, v0
	v_mov_b32_e32 v91, v1
	v_lshl_add_u64 v[90:91], v[90:91], 1, s[6:7]
	global_load_dwordx4 v[102:105], v[90:91], off
	v_add_u32_e32 v90, 0x6080, v0
	v_mov_b32_e32 v91, v1
	v_ashrrev_i32_e32 v183, 31, v182
	v_lshl_add_u64 v[90:91], v[90:91], 1, s[6:7]
	v_lshl_add_u64 v[178:179], v[182:183], 2, s[20:21]
	global_load_dwordx4 v[90:93], v[90:91], off
	s_nop 0
	global_load_dwordx4 v[162:165], v[178:179], off offset:16
	global_load_dwordx4 v[196:199], v[178:179], off
	v_ashrrev_i32_e32 v181, 31, v180
	s_mov_b32 s1, 0x48000
	s_mov_b64 s[28:29], 0x48000
	global_load_dwordx4 v[226:229], v[178:179], off
	global_load_dwordx4 v[230:233], v[178:179], off offset:16
	global_load_dwordx4 v[234:237], v[178:179], off offset:512
	global_load_dwordx4 v[204:207], v[178:179], off offset:528
	s_waitcnt vmcnt(0) lgkmcnt(0)
	v_lshlrev_b32_e32 v200, 16, v158
	v_and_b32_e32 v158, 0xffff0000, v158
	v_add_f32_e32 v142, v142, v162
	v_add_f32_e32 v147, v147, v197
	v_mul_f32_e32 v147, 0xbfb8aa3b, v147
	v_add_f32_e32 v148, v148, v198
	v_exp_f32_e32 v147, v147
	v_mul_f32_e32 v148, 0xbfb8aa3b, v148
	v_add_f32_e32 v149, v149, v199
	v_exp_f32_e32 v148, v148
	v_mul_f32_e32 v149, 0xbfb8aa3b, v149
	v_exp_f32_e32 v149, v149
	v_mul_f32_e32 v142, 0xbfb8aa3b, v142
	v_add_f32_e32 v143, v143, v163
	v_exp_f32_e32 v142, v142
	v_mul_f32_e32 v143, 0xbfb8aa3b, v143
	v_add_f32_e32 v147, 1.0, v147
	v_exp_f32_e32 v143, v143
	v_rcp_f32_e32 v147, v147
	v_add_f32_e32 v148, 1.0, v148
	v_rcp_f32_e32 v148, v148
	v_add_f32_e32 v149, 1.0, v149
	v_rcp_f32_e32 v149, v149
	v_add_f32_e32 v142, 1.0, v142
	v_rcp_f32_e32 v142, v142
	v_add_f32_e32 v143, 1.0, v143
	v_mul_f32_e32 v147, v147, v158
	v_lshlrev_b32_e32 v158, 16, v159
	v_rcp_f32_e32 v143, v143
	v_mul_f32_e32 v148, v148, v158
	v_and_b32_e32 v158, 0xffff0000, v159
	v_mul_f32_e32 v149, v149, v158
	v_lshlrev_b32_e32 v158, 16, v160
	v_mul_f32_e32 v158, v142, v158
	v_and_b32_e32 v142, 0xffff0000, v160
	v_mul_f32_e32 v159, v143, v142
	v_add_f32_e32 v143, v144, v164
	v_mul_f32_e32 v143, 0xbfb8aa3b, v143
	v_exp_f32_e32 v143, v143
	v_add_f32_e32 v146, v146, v196
	v_lshlrev_b32_e32 v142, 16, v161
	v_mul_f32_e32 v146, 0xbfb8aa3b, v146
	v_add_f32_e32 v143, 1.0, v143
	v_rcp_f32_e32 v143, v143
	v_exp_f32_e32 v146, v146
	v_lshlrev_b32_e32 v162, 16, v154
	v_and_b32_e32 v154, 0xffff0000, v154
	v_mul_f32_e32 v160, v143, v142
	v_add_f32_e32 v143, v145, v165
	v_mul_f32_e32 v143, 0xbfb8aa3b, v143
	v_exp_f32_e32 v143, v143
	v_add_f32_e32 v146, 1.0, v146
	v_rcp_f32_e32 v146, v146
	v_and_b32_e32 v142, 0xffff0000, v161
	v_add_f32_e32 v143, 1.0, v143
	v_rcp_f32_e32 v143, v143
	v_mul_f32_e32 v146, v146, v200
	v_mul_f32_e32 v145, v143, v142
	v_cvt_pk_bf16_f32 v142, v146, v147
	v_lshlrev_b64 v[146:147], 11, v[180:181]
	v_cvt_pk_bf16_f32 v143, v148, v149
	v_lshl_add_u64 v[146:147], s[18:19], 0, v[146:147]
	v_lshlrev_b64 v[148:149], 1, v[182:183]
	v_lshl_add_u64 v[146:147], v[146:147], 0, v[148:149]
	v_cvt_pk_bf16_f32 v144, v158, v159
	v_cvt_pk_bf16_f32 v145, v160, v145
	global_store_dwordx4 v[146:147], v[142:145], off
	s_nop 1
	v_mov_b32_e32 v142, v204
	v_mov_b32_e32 v143, v205
	v_mov_b32_e32 v144, v206
	v_mov_b32_e32 v145, v207
	v_mov_b32_e32 v158, v234
	v_mov_b32_e32 v159, v235
	v_mov_b32_e32 v160, v236
	v_mov_b32_e32 v161, v237
	v_add_f32_e32 v130, v130, v142
	v_add_f32_e32 v139, v139, v159
	v_mul_f32_e32 v139, 0xbfb8aa3b, v139
	v_add_f32_e32 v140, v140, v160
	v_exp_f32_e32 v139, v139
	v_mul_f32_e32 v140, 0xbfb8aa3b, v140
	v_add_f32_e32 v141, v141, v161
	v_exp_f32_e32 v140, v140
	v_mul_f32_e32 v141, 0xbfb8aa3b, v141
	v_exp_f32_e32 v141, v141
	v_mul_f32_e32 v130, 0xbfb8aa3b, v130
	v_add_f32_e32 v131, v131, v143
	v_exp_f32_e32 v130, v130
	v_mul_f32_e32 v131, 0xbfb8aa3b, v131
	v_add_f32_e32 v139, 1.0, v139
	v_exp_f32_e32 v131, v131
	v_rcp_f32_e32 v139, v139
	v_add_f32_e32 v140, 1.0, v140
	v_rcp_f32_e32 v140, v140
	v_add_f32_e32 v141, 1.0, v141
	v_rcp_f32_e32 v141, v141
	v_add_f32_e32 v130, 1.0, v130
	v_rcp_f32_e32 v130, v130
	v_add_f32_e32 v131, 1.0, v131
	v_mul_f32_e32 v139, v139, v154
	v_lshlrev_b32_e32 v154, 16, v155
	v_rcp_f32_e32 v131, v131
	v_mul_f32_e32 v140, v140, v154
	v_and_b32_e32 v154, 0xffff0000, v155
	v_mul_f32_e32 v141, v141, v154
	v_lshlrev_b32_e32 v154, 16, v156
	v_mul_f32_e32 v142, v130, v154
	v_and_b32_e32 v130, 0xffff0000, v156
	v_mul_f32_e32 v143, v131, v130
	v_add_f32_e32 v131, v132, v144
	v_mul_f32_e32 v131, 0xbfb8aa3b, v131
	v_exp_f32_e32 v131, v131
	v_lshlrev_b32_e32 v130, 16, v157
	v_add_f32_e32 v138, v138, v158
	v_mul_f32_e32 v138, 0xbfb8aa3b, v138
	v_add_f32_e32 v131, 1.0, v131
	v_rcp_f32_e32 v131, v131
	v_exp_f32_e32 v138, v138
	v_mul_f32_e32 v144, v131, v130
	v_add_f32_e32 v131, v133, v145
; __device__ __forceinline__ unsigned cvt_pk_bf16(float lo, float hi) { unsigned r; asm volatile("v_cvt_pk_bf16_f32 %0, %1, %2" : "=v"(r) : "v"(lo), "v"(hi)); return r; }
; __device__ __forceinline__ float fast_sigmoid(float x) { return __builtin_amdgcn_rcpf(1.0f + __expf(-x)); }
;     __device__ __forceinline__ void operator()(const f32x4 (&acc)[2][2][4][2], const Unit& u, int wr, int wc, int fr, int fq, PG8_LAS unsigned char* ldsb) const {
;     ...
;             for (int m = 0; m < 4; ++m) {
;                 const int row = row0 + ai * HALF + m * 16;
; #pragma unroll
;                 for (int bj = 0; bj < 2; ++bj) {
;                     const int c = col0 + bj * HALF;
;                     const u32x4 zw = zv[m][bj];
;                     float v[8];
; #pragma unroll
;                     for (int n = 0; n < 2; ++n)
; #pragma unroll
;                         for (int i = 0; i < 4; ++i) { const int e = n * 4 + i; const unsigned wd = zw[e >> 1];
;                             const float z = __uint_as_float((e & 1) ? (wd & 0xffff0000u) : (wd << 16));
;                             v[e] = z * fast_sigmoid(acc[ai][bj][m][n][i] + bias[c + e]); }
;                     u32x4 w; w.x = cvt_pk_bf16(v[0], v[1]); w.y = cvt_pk_bf16(v[2], v[3]); w.z = cvt_pk_bf16(v[4], v[5]); w.w = cvt_pk_bf16(v[6], v[7]);
;                     *(u32x4*)(O + (size_t)row * ldo + c) = w;
;                 }
;             }
	v_mul_f32_e32 v131, 0xbfb8aa3b, v131
	v_exp_f32_e32 v131, v131
	v_add_f32_e32 v138, 1.0, v138
	v_rcp_f32_e32 v138, v138
	v_and_b32_e32 v130, 0xffff0000, v157
	v_add_f32_e32 v131, 1.0, v131
	v_rcp_f32_e32 v131, v131
	v_mul_f32_e32 v138, v138, v162
	v_mul_f32_e32 v133, v131, v130
	v_cvt_pk_bf16_f32 v130, v138, v139
	v_cvt_pk_bf16_f32 v131, v140, v141
	v_cvt_pk_bf16_f32 v132, v142, v143
	v_cvt_pk_bf16_f32 v133, v144, v133
	global_store_dwordx4 v[146:147], v[130:133], off offset:256
	s_nop 1
	v_mov_b32_e32 v138, v230
	v_mov_b32_e32 v139, v231
	v_mov_b32_e32 v140, v232
	v_mov_b32_e32 v141, v233
	v_mov_b32_e32 v142, v226
	v_mov_b32_e32 v143, v227
	v_mov_b32_e32 v144, v228
	v_mov_b32_e32 v145, v229
	v_lshlrev_b32_e32 v132, 16, v150
	v_or_b32_e32 v130, 16, v180
	v_ashrrev_i32_e32 v131, 31, v130
	v_add_f32_e32 v118, v118, v138
	v_add_f32_e32 v122, v122, v142
	v_mul_f32_e32 v122, 0xbfb8aa3b, v122
	v_add_f32_e32 v123, v123, v143
	v_exp_f32_e32 v122, v122
	v_mul_f32_e32 v123, 0xbfb8aa3b, v123
	v_add_f32_e32 v124, v124, v144
	v_exp_f32_e32 v123, v123
	v_mul_f32_e32 v124, 0xbfb8aa3b, v124
	v_add_f32_e32 v125, v125, v145
	v_exp_f32_e32 v124, v124
	v_mul_f32_e32 v125, 0xbfb8aa3b, v125
	v_exp_f32_e32 v125, v125
	v_mul_f32_e32 v118, 0xbfb8aa3b, v118
	v_add_f32_e32 v119, v119, v139
	v_add_f32_e32 v122, 1.0, v122
	v_exp_f32_e32 v118, v118
	v_mul_f32_e32 v119, 0xbfb8aa3b, v119
	v_rcp_f32_e32 v122, v122
	v_add_f32_e32 v123, 1.0, v123
	v_exp_f32_e32 v119, v119
	v_rcp_f32_e32 v123, v123
	v_add_f32_e32 v124, 1.0, v124
	v_rcp_f32_e32 v124, v124
	v_add_f32_e32 v125, 1.0, v125
	v_rcp_f32_e32 v125, v125
	v_add_f32_e32 v118, 1.0, v118
	v_mul_f32_e32 v122, v122, v132
	v_and_b32_e32 v132, 0xffff0000, v150
	v_rcp_f32_e32 v118, v118
	v_add_f32_e32 v119, 1.0, v119
	v_mul_f32_e32 v123, v123, v132
	v_lshlrev_b32_e32 v132, 16, v151
	v_rcp_f32_e32 v119, v119
	v_mul_f32_e32 v124, v124, v132
	v_and_b32_e32 v132, 0xffff0000, v151
	v_mul_f32_e32 v125, v125, v132
	v_lshlrev_b32_e32 v132, 16, v152
	v_mul_f32_e32 v132, v118, v132
	v_and_b32_e32 v118, 0xffff0000, v152
	v_mul_f32_e32 v133, v119, v118
	v_add_f32_e32 v119, v120, v140
	v_mul_f32_e32 v119, 0xbfb8aa3b, v119
	v_exp_f32_e32 v119, v119
	v_lshlrev_b32_e32 v118, 16, v153
	v_add_f32_e32 v119, 1.0, v119
	v_rcp_f32_e32 v119, v119
	s_nop 0
	v_mul_f32_e32 v138, v119, v118
	v_add_f32_e32 v119, v121, v141
	v_mul_f32_e32 v119, 0xbfb8aa3b, v119
	v_exp_f32_e32 v119, v119
	v_and_b32_e32 v118, 0xffff0000, v153
	v_add_f32_e32 v119, 1.0, v119
	v_rcp_f32_e32 v119, v119
	s_nop 0
	v_mul_f32_e32 v121, v119, v118
	v_cvt_pk_bf16_f32 v118, v122, v123
	v_lshlrev_b64 v[122:123], 11, v[130:131]
	v_lshl_add_u64 v[122:123], s[18:19], 0, v[122:123]
	v_lshl_add_u64 v[122:123], v[122:123], 0, v[148:149]
	v_cvt_pk_bf16_f32 v119, v124, v125
	v_cvt_pk_bf16_f32 v120, v132, v133
	v_cvt_pk_bf16_f32 v121, v138, v121
	global_store_dwordx4 v[122:123], v[118:121], off
	s_nop 1
	v_mov_b32_e32 v118, v204
	v_mov_b32_e32 v119, v205
	v_mov_b32_e32 v120, v206
	v_mov_b32_e32 v121, v207
	v_mov_b32_e32 v130, v234
	v_mov_b32_e32 v131, v235
	v_mov_b32_e32 v132, v236
	v_mov_b32_e32 v133, v237
	v_lshlrev_b32_e32 v124, 16, v134
	v_add_f32_e32 v106, v106, v118
	v_add_f32_e32 v114, v114, v130
	v_mul_f32_e32 v114, 0xbfb8aa3b, v114
	v_add_f32_e32 v115, v115, v131
	v_exp_f32_e32 v114, v114
	v_mul_f32_e32 v115, 0xbfb8aa3b, v115
	v_add_f32_e32 v116, v116, v132
	v_exp_f32_e32 v115, v115
	v_mul_f32_e32 v116, 0xbfb8aa3b, v116
	v_add_f32_e32 v117, v117, v133
	v_exp_f32_e32 v116, v116
	v_mul_f32_e32 v117, 0xbfb8aa3b, v117
	v_exp_f32_e32 v117, v117
	v_mul_f32_e32 v106, 0xbfb8aa3b, v106
	v_add_f32_e32 v107, v107, v119
	v_add_f32_e32 v114, 1.0, v114
	v_exp_f32_e32 v106, v106
	v_mul_f32_e32 v107, 0xbfb8aa3b, v107
	v_rcp_f32_e32 v114, v114
	v_add_f32_e32 v115, 1.0, v115
	v_exp_f32_e32 v107, v107
	v_rcp_f32_e32 v115, v115
	v_add_f32_e32 v116, 1.0, v116
	v_rcp_f32_e32 v116, v116
	v_add_f32_e32 v117, 1.0, v117
	v_rcp_f32_e32 v117, v117
	v_add_f32_e32 v106, 1.0, v106
	v_mul_f32_e32 v114, v114, v124
	v_and_b32_e32 v124, 0xffff0000, v134
	v_rcp_f32_e32 v106, v106
	v_add_f32_e32 v107, 1.0, v107
	v_mul_f32_e32 v115, v115, v124
	v_lshlrev_b32_e32 v124, 16, v135
	v_rcp_f32_e32 v107, v107
	v_mul_f32_e32 v116, v116, v124
	v_and_b32_e32 v124, 0xffff0000, v135
	v_mul_f32_e32 v117, v117, v124
	v_lshlrev_b32_e32 v124, 16, v136
	v_mul_f32_e32 v118, v106, v124
	v_and_b32_e32 v106, 0xffff0000, v136
	v_mul_f32_e32 v119, v107, v106
	v_add_f32_e32 v107, v108, v120
	v_mul_f32_e32 v107, 0xbfb8aa3b, v107
	v_exp_f32_e32 v107, v107
	v_lshlrev_b32_e32 v106, 16, v137
	v_add_f32_e32 v107, 1.0, v107
	v_rcp_f32_e32 v107, v107
	s_nop 0
	v_mul_f32_e32 v120, v107, v106
	v_add_f32_e32 v107, v109, v121
	v_mul_f32_e32 v107, 0xbfb8aa3b, v107
	v_exp_f32_e32 v107, v107
	v_and_b32_e32 v106, 0xffff0000, v137
	v_add_f32_e32 v107, 1.0, v107
	v_rcp_f32_e32 v107, v107
	s_nop 0
	v_mul_f32_e32 v109, v107, v106
	v_cvt_pk_bf16_f32 v106, v114, v115
	v_cvt_pk_bf16_f32 v107, v116, v117
	v_cvt_pk_bf16_f32 v108, v118, v119
	v_cvt_pk_bf16_f32 v109, v120, v109
	global_store_dwordx4 v[122:123], v[106:109], off offset:256
	s_nop 1
	v_mov_b32_e32 v114, v230
	v_mov_b32_e32 v115, v231
	v_mov_b32_e32 v116, v232
	v_mov_b32_e32 v117, v233
	v_mov_b32_e32 v118, v226
	v_mov_b32_e32 v119, v227
	v_mov_b32_e32 v120, v228
	v_mov_b32_e32 v121, v229
	v_lshlrev_b32_e32 v108, 16, v126
	v_or_b32_e32 v106, 32, v180
	v_ashrrev_i32_e32 v107, 31, v106
	v_add_f32_e32 v94, v94, v114
	v_add_f32_e32 v98, v98, v118
	v_mul_f32_e32 v98, 0xbfb8aa3b, v98
	v_add_f32_e32 v99, v99, v119
	v_exp_f32_e32 v98, v98
	v_mul_f32_e32 v99, 0xbfb8aa3b, v99
	v_add_f32_e32 v100, v100, v120
; __device__ __forceinline__ unsigned cvt_pk_bf16(float lo, float hi) { unsigned r; asm volatile("v_cvt_pk_bf16_f32 %0, %1, %2" : "=v"(r) : "v"(lo), "v"(hi)); return r; }
; __device__ __forceinline__ float fast_sigmoid(float x) { return __builtin_amdgcn_rcpf(1.0f + __expf(-x)); }
;     __device__ __forceinline__ void operator()(const f32x4 (&acc)[2][2][4][2], const Unit& u, int wr, int wc, int fr, int fq, PG8_LAS unsigned char* ldsb) const {
;     ...
;             for (int m = 0; m < 4; ++m) {
;                 const int row = row0 + ai * HALF + m * 16;
; #pragma unroll
;                 for (int bj = 0; bj < 2; ++bj) {
;                     const int c = col0 + bj * HALF;
;                     const u32x4 zw = zv[m][bj];
;                     float v[8];
; #pragma unroll
;                     for (int n = 0; n < 2; ++n)
; #pragma unroll
;                         for (int i = 0; i < 4; ++i) { const int e = n * 4 + i; const unsigned wd = zw[e >> 1];
;                             const float z = __uint_as_float((e & 1) ? (wd & 0xffff0000u) : (wd << 16));
;                             v[e] = z * fast_sigmoid(acc[ai][bj][m][n][i] + bias[c + e]); }
;                     u32x4 w; w.x = cvt_pk_bf16(v[0], v[1]); w.y = cvt_pk_bf16(v[2], v[3]); w.z = cvt_pk_bf16(v[4], v[5]); w.w = cvt_pk_bf16(v[6], v[7]);
;                     *(u32x4*)(O + (size_t)row * ldo + c) = w;
;                 }
;             }
	v_exp_f32_e32 v99, v99
	v_mul_f32_e32 v100, 0xbfb8aa3b, v100
	v_add_f32_e32 v101, v101, v121
	v_exp_f32_e32 v100, v100
	v_mul_f32_e32 v101, 0xbfb8aa3b, v101
	v_exp_f32_e32 v101, v101
	v_mul_f32_e32 v94, 0xbfb8aa3b, v94
	v_add_f32_e32 v95, v95, v115
	v_add_f32_e32 v98, 1.0, v98
	v_exp_f32_e32 v94, v94
	v_mul_f32_e32 v95, 0xbfb8aa3b, v95
	v_rcp_f32_e32 v98, v98
	v_add_f32_e32 v99, 1.0, v99
	v_exp_f32_e32 v95, v95
	v_rcp_f32_e32 v99, v99
	v_add_f32_e32 v100, 1.0, v100
	v_rcp_f32_e32 v100, v100
	v_add_f32_e32 v101, 1.0, v101
	v_rcp_f32_e32 v101, v101
	v_add_f32_e32 v94, 1.0, v94
	v_mul_f32_e32 v98, v98, v108
	v_and_b32_e32 v108, 0xffff0000, v126
	v_rcp_f32_e32 v94, v94
	v_add_f32_e32 v95, 1.0, v95
	v_mul_f32_e32 v99, v99, v108
	v_lshlrev_b32_e32 v108, 16, v127
	v_rcp_f32_e32 v95, v95
	v_mul_f32_e32 v100, v100, v108
	v_and_b32_e32 v108, 0xffff0000, v127
	v_mul_f32_e32 v101, v101, v108
	v_lshlrev_b32_e32 v108, 16, v128
	v_mul_f32_e32 v108, v94, v108
	v_and_b32_e32 v94, 0xffff0000, v128
	v_mul_f32_e32 v109, v95, v94
	v_add_f32_e32 v95, v96, v116
	v_mul_f32_e32 v95, 0xbfb8aa3b, v95
	v_exp_f32_e32 v95, v95
	v_lshlrev_b32_e32 v94, 16, v129
	v_add_f32_e32 v95, 1.0, v95
	v_rcp_f32_e32 v95, v95
	s_nop 0
	v_mul_f32_e32 v114, v95, v94
	v_add_f32_e32 v95, v97, v117
	v_mul_f32_e32 v95, 0xbfb8aa3b, v95
	v_exp_f32_e32 v95, v95
	v_and_b32_e32 v94, 0xffff0000, v129
	v_add_f32_e32 v95, 1.0, v95
	v_rcp_f32_e32 v95, v95
	s_nop 0
	v_mul_f32_e32 v97, v95, v94
	v_cvt_pk_bf16_f32 v94, v98, v99
	v_lshlrev_b64 v[98:99], 11, v[106:107]
	v_lshl_add_u64 v[98:99], s[18:19], 0, v[98:99]
	v_lshl_add_u64 v[98:99], v[98:99], 0, v[148:149]
	v_cvt_pk_bf16_f32 v95, v100, v101
	v_cvt_pk_bf16_f32 v96, v108, v109
	v_cvt_pk_bf16_f32 v97, v114, v97
	global_store_dwordx4 v[98:99], v[94:97], off
	s_nop 1
	v_mov_b32_e32 v94, v204
	v_mov_b32_e32 v95, v205
	v_mov_b32_e32 v96, v206
	v_mov_b32_e32 v97, v207
	v_mov_b32_e32 v106, v234
	v_mov_b32_e32 v107, v235
	v_mov_b32_e32 v108, v236
	v_mov_b32_e32 v109, v237
	v_lshlrev_b32_e32 v100, 16, v110
	v_add_f32_e32 v82, v82, v94
	v_add_f32_e32 v86, v86, v106
	v_mul_f32_e32 v86, 0xbfb8aa3b, v86
	v_add_f32_e32 v87, v87, v107
	v_exp_f32_e32 v86, v86
	v_mul_f32_e32 v87, 0xbfb8aa3b, v87
	v_add_f32_e32 v88, v88, v108
	v_exp_f32_e32 v87, v87
	v_mul_f32_e32 v88, 0xbfb8aa3b, v88
	v_add_f32_e32 v89, v89, v109
	v_exp_f32_e32 v88, v88
	v_mul_f32_e32 v89, 0xbfb8aa3b, v89
	v_exp_f32_e32 v89, v89
	v_mul_f32_e32 v82, 0xbfb8aa3b, v82
	v_add_f32_e32 v83, v83, v95
	v_add_f32_e32 v86, 1.0, v86
	v_exp_f32_e32 v82, v82
	v_mul_f32_e32 v83, 0xbfb8aa3b, v83
	v_rcp_f32_e32 v86, v86
	v_add_f32_e32 v87, 1.0, v87
	v_exp_f32_e32 v83, v83
	v_rcp_f32_e32 v87, v87
	v_add_f32_e32 v88, 1.0, v88
	v_rcp_f32_e32 v88, v88
	v_add_f32_e32 v89, 1.0, v89
	v_rcp_f32_e32 v89, v89
	v_add_f32_e32 v82, 1.0, v82
	v_mul_f32_e32 v86, v86, v100
	v_and_b32_e32 v100, 0xffff0000, v110
	v_rcp_f32_e32 v82, v82
	v_add_f32_e32 v83, 1.0, v83
	v_mul_f32_e32 v87, v87, v100
	v_lshlrev_b32_e32 v100, 16, v111
	v_rcp_f32_e32 v83, v83
	v_mul_f32_e32 v88, v88, v100
	v_and_b32_e32 v100, 0xffff0000, v111
	v_mul_f32_e32 v89, v89, v100
	v_lshlrev_b32_e32 v100, 16, v112
	v_mul_f32_e32 v94, v82, v100
	v_and_b32_e32 v82, 0xffff0000, v112
	v_mul_f32_e32 v95, v83, v82
	v_add_f32_e32 v83, v84, v96
	v_mul_f32_e32 v83, 0xbfb8aa3b, v83
	v_exp_f32_e32 v83, v83
	v_lshlrev_b32_e32 v82, 16, v113
	v_add_f32_e32 v83, 1.0, v83
	v_rcp_f32_e32 v83, v83
	s_nop 0
	v_mul_f32_e32 v96, v83, v82
	v_add_f32_e32 v83, v85, v97
	v_mul_f32_e32 v83, 0xbfb8aa3b, v83
	v_exp_f32_e32 v83, v83
	v_and_b32_e32 v82, 0xffff0000, v113
	v_add_f32_e32 v83, 1.0, v83
	v_rcp_f32_e32 v83, v83
	s_nop 0
	v_mul_f32_e32 v85, v83, v82
	v_cvt_pk_bf16_f32 v82, v86, v87
	v_cvt_pk_bf16_f32 v83, v88, v89
	v_cvt_pk_bf16_f32 v84, v94, v95
	v_cvt_pk_bf16_f32 v85, v96, v85
	global_store_dwordx4 v[98:99], v[82:85], off offset:256
	s_nop 1
	v_mov_b32_e32 v84, v230
	v_mov_b32_e32 v85, v231
	v_mov_b32_e32 v86, v232
	v_mov_b32_e32 v87, v233
	v_mov_b32_e32 v94, v226
	v_mov_b32_e32 v95, v227
	v_mov_b32_e32 v96, v228
	v_mov_b32_e32 v97, v229
	v_lshlrev_b32_e32 v88, 16, v102
	v_or_b32_e32 v82, 48, v180
	v_ashrrev_i32_e32 v83, 31, v82
	v_add_f32_e32 v74, v74, v84
	v_add_f32_e32 v78, v78, v94
	v_mul_f32_e32 v78, 0xbfb8aa3b, v78
	v_add_f32_e32 v79, v79, v95
	v_exp_f32_e32 v78, v78
	v_mul_f32_e32 v79, 0xbfb8aa3b, v79
	v_add_f32_e32 v80, v80, v96
	v_exp_f32_e32 v79, v79
	v_mul_f32_e32 v80, 0xbfb8aa3b, v80
	v_add_f32_e32 v81, v81, v97
	v_exp_f32_e32 v80, v80
	v_mul_f32_e32 v81, 0xbfb8aa3b, v81
	v_exp_f32_e32 v81, v81
	v_mul_f32_e32 v74, 0xbfb8aa3b, v74
	v_add_f32_e32 v75, v75, v85
	v_add_f32_e32 v78, 1.0, v78
	v_exp_f32_e32 v74, v74
	v_mul_f32_e32 v75, 0xbfb8aa3b, v75
	v_rcp_f32_e32 v78, v78
	v_add_f32_e32 v79, 1.0, v79
	v_exp_f32_e32 v75, v75
	v_rcp_f32_e32 v79, v79
	v_add_f32_e32 v80, 1.0, v80
	v_rcp_f32_e32 v80, v80
	v_add_f32_e32 v81, 1.0, v81
	v_rcp_f32_e32 v81, v81
	v_add_f32_e32 v74, 1.0, v74
	v_mul_f32_e32 v78, v78, v88
	v_and_b32_e32 v88, 0xffff0000, v102
	v_rcp_f32_e32 v74, v74
	v_add_f32_e32 v75, 1.0, v75
	v_mul_f32_e32 v79, v79, v88
	v_lshlrev_b32_e32 v88, 16, v103
	v_rcp_f32_e32 v75, v75
	v_mul_f32_e32 v80, v80, v88
	v_and_b32_e32 v88, 0xffff0000, v103
	v_mul_f32_e32 v81, v81, v88
	v_lshlrev_b32_e32 v88, 16, v104
	v_mul_f32_e32 v84, v74, v88
	v_and_b32_e32 v74, 0xffff0000, v104
	v_mul_f32_e32 v85, v75, v74
	v_add_f32_e32 v75, v76, v86
	v_mul_f32_e32 v75, 0xbfb8aa3b, v75
	v_exp_f32_e32 v75, v75
	v_lshlrev_b32_e32 v74, 16, v105
	v_add_f32_e32 v75, 1.0, v75
	v_rcp_f32_e32 v75, v75
	s_nop 0
	v_mul_f32_e32 v86, v75, v74
	v_add_f32_e32 v75, v77, v87
	v_mul_f32_e32 v75, 0xbfb8aa3b, v75
; __device__ __forceinline__ unsigned cvt_pk_bf16(float lo, float hi) { unsigned r; asm volatile("v_cvt_pk_bf16_f32 %0, %1, %2" : "=v"(r) : "v"(lo), "v"(hi)); return r; }
; __device__ __forceinline__ float fast_sigmoid(float x) { return __builtin_amdgcn_rcpf(1.0f + __expf(-x)); }
;     __device__ __forceinline__ void operator()(const f32x4 (&acc)[2][2][4][2], const Unit& u, int wr, int wc, int fr, int fq, PG8_LAS unsigned char* ldsb) const {
;     ...
;             u32x4 zv[4][2];
; #pragma unroll
;             for (int m = 0; m < 4; ++m)
; #pragma unroll
;                 for (int bj = 0; bj < 2; ++bj) zv[m][bj] = *(const u32x4*)(Zs + ((unsigned)(row0 + ai * HALF + m * 16) * 512u + (unsigned)(col0 + bj * HALF)));
; #pragma unroll
;             for (int m = 0; m < 4; ++m) {
;                 const int row = row0 + ai * HALF + m * 16;
; #pragma unroll
;                 for (int bj = 0; bj < 2; ++bj) {
;                     const int c = col0 + bj * HALF;
;                     const u32x4 zw = zv[m][bj];
;                     float v[8];
; #pragma unroll
;                     for (int n = 0; n < 2; ++n)
; #pragma unroll
;                         for (int i = 0; i < 4; ++i) { const int e = n * 4 + i; const unsigned wd = zw[e >> 1];
;                             const float z = __uint_as_float((e & 1) ? (wd & 0xffff0000u) : (wd << 16));
;                             v[e] = z * fast_sigmoid(acc[ai][bj][m][n][i] + bias[c + e]); }
;                     u32x4 w; w.x = cvt_pk_bf16(v[0], v[1]); w.y = cvt_pk_bf16(v[2], v[3]); w.z = cvt_pk_bf16(v[4], v[5]); w.w = cvt_pk_bf16(v[6], v[7]);
;                     *(u32x4*)(O + (size_t)row * ldo + c) = w;
;                 }
;             }
	v_exp_f32_e32 v75, v75
	v_and_b32_e32 v74, 0xffff0000, v105
	v_add_f32_e32 v75, 1.0, v75
	v_rcp_f32_e32 v75, v75
	s_nop 0
	v_mul_f32_e32 v77, v75, v74
	v_cvt_pk_bf16_f32 v74, v78, v79
	v_lshlrev_b64 v[78:79], 11, v[82:83]
	v_lshl_add_u64 v[78:79], s[18:19], 0, v[78:79]
	v_lshl_add_u64 v[78:79], v[78:79], 0, v[148:149]
	v_cvt_pk_bf16_f32 v75, v80, v81
	v_cvt_pk_bf16_f32 v76, v84, v85
	v_cvt_pk_bf16_f32 v77, v86, v77
	global_store_dwordx4 v[78:79], v[74:77], off
	s_nop 1
	v_mov_b32_e32 v74, v204
	v_mov_b32_e32 v75, v205
	v_mov_b32_e32 v76, v206
	v_mov_b32_e32 v77, v207
	v_mov_b32_e32 v80, v234
	v_mov_b32_e32 v81, v235
	v_mov_b32_e32 v82, v236
	v_mov_b32_e32 v83, v237
	v_lshlrev_b32_e32 v84, 16, v90
	v_add_f32_e32 v66, v66, v74
	v_add_f32_e32 v71, v71, v81
	v_mul_f32_e32 v71, 0xbfb8aa3b, v71
	v_add_f32_e32 v72, v72, v82
	v_exp_f32_e32 v71, v71
	v_mul_f32_e32 v72, 0xbfb8aa3b, v72
	v_add_f32_e32 v73, v73, v83
	v_exp_f32_e32 v72, v72
	v_mul_f32_e32 v73, 0xbfb8aa3b, v73
	v_exp_f32_e32 v73, v73
	v_mul_f32_e32 v66, 0xbfb8aa3b, v66
	v_add_f32_e32 v67, v67, v75
	v_exp_f32_e32 v66, v66
	v_mul_f32_e32 v67, 0xbfb8aa3b, v67
	v_add_f32_e32 v71, 1.0, v71
	v_exp_f32_e32 v67, v67
	v_rcp_f32_e32 v71, v71
	v_add_f32_e32 v72, 1.0, v72
	v_rcp_f32_e32 v72, v72
	v_add_f32_e32 v73, 1.0, v73
	v_rcp_f32_e32 v73, v73
	v_add_f32_e32 v66, 1.0, v66
	v_add_f32_e32 v70, v70, v80
	v_and_b32_e32 v80, 0xffff0000, v90
	v_rcp_f32_e32 v66, v66
	v_add_f32_e32 v67, 1.0, v67
	v_mul_f32_e32 v71, v71, v80
	v_lshlrev_b32_e32 v80, 16, v91
	v_rcp_f32_e32 v67, v67
	v_mul_f32_e32 v72, v72, v80
	v_and_b32_e32 v80, 0xffff0000, v91
	v_mul_f32_e32 v73, v73, v80
	v_lshlrev_b32_e32 v80, 16, v92
	v_mul_f32_e32 v74, v66, v80
	v_and_b32_e32 v66, 0xffff0000, v92
	v_mul_f32_e32 v75, v67, v66
	v_add_f32_e32 v67, v68, v76
	v_mul_f32_e32 v67, 0xbfb8aa3b, v67
	v_exp_f32_e32 v67, v67
	v_lshlrev_b32_e32 v66, 16, v93
	v_mul_f32_e32 v70, 0xbfb8aa3b, v70
	v_exp_f32_e32 v70, v70
	v_add_f32_e32 v67, 1.0, v67
	v_rcp_f32_e32 v67, v67
	v_add_f32_e32 v70, 1.0, v70
	v_rcp_f32_e32 v70, v70
	v_mul_f32_e32 v76, v67, v66
	v_add_f32_e32 v67, v69, v77
	v_mul_f32_e32 v67, 0xbfb8aa3b, v67
	v_exp_f32_e32 v67, v67
	v_and_b32_e32 v66, 0xffff0000, v93
	v_mul_f32_e32 v70, v70, v84
	v_add_f32_e32 v67, 1.0, v67
	v_rcp_f32_e32 v67, v67
	s_nop 0
	v_mul_f32_e32 v69, v67, v66
	v_cvt_pk_bf16_f32 v66, v70, v71
	v_cvt_pk_bf16_f32 v67, v72, v73
	v_cvt_pk_bf16_f32 v68, v74, v75
	v_cvt_pk_bf16_f32 v69, v76, v69
	global_store_dwordx4 v[78:79], v[66:69], off offset:256
	s_nop 1
	v_add_u32_e32 v66, 0x10000, v0
	v_mov_b32_e32 v67, v1
	v_lshl_add_u64 v[66:67], v[66:67], 1, s[6:7]
	global_load_dwordx4 v[94:97], v[66:67], off
	v_add_u32_e32 v66, 0x10080, v0
	v_mov_b32_e32 v67, v1
	v_lshl_add_u64 v[66:67], v[66:67], 1, s[6:7]
	global_load_dwordx4 v[90:93], v[66:67], off
	v_add_u32_e32 v66, 0x12000, v0
	v_mov_b32_e32 v67, v1
	v_lshl_add_u64 v[66:67], v[66:67], 1, s[6:7]
	global_load_dwordx4 v[86:89], v[66:67], off
	v_add_u32_e32 v66, 0x12080, v0
	v_mov_b32_e32 v67, v1
	v_lshl_add_u64 v[66:67], v[66:67], 1, s[6:7]
	global_load_dwordx4 v[82:85], v[66:67], off
	v_add_u32_e32 v66, 0x14000, v0
	v_mov_b32_e32 v67, v1
	v_lshl_add_u64 v[66:67], v[66:67], 1, s[6:7]
	global_load_dwordx4 v[78:81], v[66:67], off
	v_add_u32_e32 v66, 0x14080, v0
	v_mov_b32_e32 v67, v1
	v_lshl_add_u64 v[66:67], v[66:67], 1, s[6:7]
	global_load_dwordx4 v[74:77], v[66:67], off
	v_add_u32_e32 v66, 0x16000, v0
	v_mov_b32_e32 v67, v1
	v_lshl_add_u64 v[66:67], v[66:67], 1, s[6:7]
	v_add_u32_e32 v0, 0x16080, v0
	global_load_dwordx4 v[70:73], v[66:67], off
	v_lshl_add_u64 v[66:67], v[0:1], 1, s[6:7]
	global_load_dwordx4 v[66:69], v[66:67], off
	s_nop 0
	global_load_dwordx4 v[98:101], v[178:179], off offset:16
	global_load_dwordx4 v[102:105], v[178:179], off
	s_waitcnt vmcnt(0) lgkmcnt(0)
	v_lshlrev_b32_e32 v0, 16, v94
	v_add_f32_e32 v58, v58, v98
	v_add_f32_e32 v62, v62, v102
	v_mul_f32_e32 v62, 0xbfb8aa3b, v62
	v_add_f32_e32 v63, v63, v103
	v_exp_f32_e32 v62, v62
	v_mul_f32_e32 v63, 0xbfb8aa3b, v63
	v_add_f32_e32 v64, v64, v104
	v_exp_f32_e32 v63, v63
	v_mul_f32_e32 v64, 0xbfb8aa3b, v64
	v_add_f32_e32 v65, v65, v105
	v_exp_f32_e32 v64, v64
	v_mul_f32_e32 v65, 0xbfb8aa3b, v65
	v_exp_f32_e32 v65, v65
	v_mul_f32_e32 v58, 0xbfb8aa3b, v58
	v_add_f32_e32 v59, v59, v99
	v_add_f32_e32 v62, 1.0, v62
	v_exp_f32_e32 v58, v58
	v_mul_f32_e32 v59, 0xbfb8aa3b, v59
	v_rcp_f32_e32 v62, v62
	v_add_f32_e32 v63, 1.0, v63
	v_exp_f32_e32 v59, v59
	v_rcp_f32_e32 v63, v63
	v_add_f32_e32 v64, 1.0, v64
	v_rcp_f32_e32 v64, v64
	v_add_f32_e32 v65, 1.0, v65
	v_rcp_f32_e32 v65, v65
	v_add_f32_e32 v58, 1.0, v58
	v_mul_f32_e32 v0, v62, v0
	v_and_b32_e32 v62, 0xffff0000, v94
	v_rcp_f32_e32 v58, v58
	v_add_f32_e32 v59, 1.0, v59
	v_mul_f32_e32 v62, v63, v62
	v_lshlrev_b32_e32 v63, 16, v95
	v_rcp_f32_e32 v59, v59
	v_mul_f32_e32 v63, v64, v63
	v_and_b32_e32 v64, 0xffff0000, v95
	v_mul_f32_e32 v64, v65, v64
	v_lshlrev_b32_e32 v65, 16, v96
	v_mul_f32_e32 v65, v58, v65
	v_and_b32_e32 v58, 0xffff0000, v96
	v_mul_f32_e32 v94, v59, v58
	v_add_f32_e32 v59, v60, v100
	v_mul_f32_e32 v59, 0xbfb8aa3b, v59
	v_exp_f32_e32 v59, v59
	v_lshlrev_b32_e32 v58, 16, v97
	v_add_f32_e32 v59, 1.0, v59
	v_rcp_f32_e32 v59, v59
	s_nop 0
	v_mul_f32_e32 v95, v59, v58
	v_add_f32_e32 v59, v61, v101
	v_mul_f32_e32 v59, 0xbfb8aa3b, v59
	v_exp_f32_e32 v59, v59
	v_and_b32_e32 v58, 0xffff0000, v97
	v_add_f32_e32 v59, 1.0, v59
	v_rcp_f32_e32 v59, v59
	s_nop 0
	v_mul_f32_e32 v61, v59, v58
	v_cvt_pk_bf16_f32 v58, v0, v62
	v_cvt_pk_bf16_f32 v59, v63, v64
	v_add_co_u32_e32 v64, vcc, s35, v146
	v_cvt_pk_bf16_f32 v60, v65, v94
	v_cvt_pk_bf16_f32 v61, v95, v61
; __device__ __forceinline__ unsigned cvt_pk_bf16(float lo, float hi) { unsigned r; asm volatile("v_cvt_pk_bf16_f32 %0, %1, %2" : "=v"(r) : "v"(lo), "v"(hi)); return r; }
; __device__ __forceinline__ float fast_sigmoid(float x) { return __builtin_amdgcn_rcpf(1.0f + __expf(-x)); }
;     __device__ __forceinline__ void operator()(const f32x4 (&acc)[2][2][4][2], const Unit& u, int wr, int wc, int fr, int fq, PG8_LAS unsigned char* ldsb) const {
;     ...
;             for (int m = 0; m < 4; ++m) {
;                 const int row = row0 + ai * HALF + m * 16;
; #pragma unroll
;                 for (int bj = 0; bj < 2; ++bj) {
;                     const int c = col0 + bj * HALF;
;                     const u32x4 zw = zv[m][bj];
;                     float v[8];
; #pragma unroll
;                     for (int n = 0; n < 2; ++n)
; #pragma unroll
;                         for (int i = 0; i < 4; ++i) { const int e = n * 4 + i; const unsigned wd = zw[e >> 1];
;                             const float z = __uint_as_float((e & 1) ? (wd & 0xffff0000u) : (wd << 16));
;                             v[e] = z * fast_sigmoid(acc[ai][bj][m][n][i] + bias[c + e]); }
;                     u32x4 w; w.x = cvt_pk_bf16(v[0], v[1]); w.y = cvt_pk_bf16(v[2], v[3]); w.z = cvt_pk_bf16(v[4], v[5]); w.w = cvt_pk_bf16(v[6], v[7]);
;                     *(u32x4*)(O + (size_t)row * ldo + c) = w;
;                 }
;             }
	v_lshlrev_b32_e32 v0, 16, v90
	s_nop 0
	v_addc_co_u32_e32 v65, vcc, 0, v147, vcc
	global_store_dwordx4 v[64:65], v[58:61], off
	s_nop 1
	v_mov_b32_e32 v58, v204
	v_mov_b32_e32 v59, v205
	v_mov_b32_e32 v60, v206
	v_mov_b32_e32 v61, v207
	v_mov_b32_e32 v94, v234
	v_mov_b32_e32 v95, v235
	v_mov_b32_e32 v96, v236
	v_mov_b32_e32 v97, v237
	v_lshl_add_u64 v[62:63], v[146:147], 0, s[72:73]
	v_add_f32_e32 v50, v50, v58
	v_add_f32_e32 v54, v54, v94
	v_mul_f32_e32 v54, 0xbfb8aa3b, v54
	v_add_f32_e32 v55, v55, v95
	v_exp_f32_e32 v54, v54
	v_mul_f32_e32 v55, 0xbfb8aa3b, v55
	v_add_f32_e32 v56, v56, v96
	v_exp_f32_e32 v55, v55
	v_mul_f32_e32 v56, 0xbfb8aa3b, v56
	v_add_f32_e32 v57, v57, v97
	v_exp_f32_e32 v56, v56
	v_mul_f32_e32 v57, 0xbfb8aa3b, v57
	v_exp_f32_e32 v57, v57
	v_mul_f32_e32 v50, 0xbfb8aa3b, v50
	v_add_f32_e32 v51, v51, v59
	v_add_f32_e32 v54, 1.0, v54
	v_exp_f32_e32 v50, v50
	v_mul_f32_e32 v51, 0xbfb8aa3b, v51
	v_rcp_f32_e32 v54, v54
	v_add_f32_e32 v55, 1.0, v55
	v_exp_f32_e32 v51, v51
	v_rcp_f32_e32 v55, v55
	v_add_f32_e32 v56, 1.0, v56
	v_rcp_f32_e32 v56, v56
	v_add_f32_e32 v57, 1.0, v57
	v_rcp_f32_e32 v57, v57
	v_add_f32_e32 v50, 1.0, v50
	v_mul_f32_e32 v0, v54, v0
	v_and_b32_e32 v54, 0xffff0000, v90
	v_rcp_f32_e32 v50, v50
	v_add_f32_e32 v51, 1.0, v51
	v_mul_f32_e32 v54, v55, v54
	v_lshlrev_b32_e32 v55, 16, v91
	v_rcp_f32_e32 v51, v51
	v_mul_f32_e32 v55, v56, v55
	v_and_b32_e32 v56, 0xffff0000, v91
	v_mul_f32_e32 v56, v57, v56
	v_lshlrev_b32_e32 v57, 16, v92
	v_mul_f32_e32 v57, v50, v57
	v_and_b32_e32 v50, 0xffff0000, v92
	v_mul_f32_e32 v58, v51, v50
	v_add_f32_e32 v51, v52, v60
	v_mul_f32_e32 v51, 0xbfb8aa3b, v51
	v_exp_f32_e32 v51, v51
	v_lshlrev_b32_e32 v50, 16, v93
	v_add_f32_e32 v51, 1.0, v51
	v_rcp_f32_e32 v51, v51
	s_nop 0
	v_mul_f32_e32 v59, v51, v50
	v_add_f32_e32 v51, v53, v61
	v_mul_f32_e32 v51, 0xbfb8aa3b, v51
	v_exp_f32_e32 v51, v51
	v_and_b32_e32 v50, 0xffff0000, v93
	v_add_f32_e32 v51, 1.0, v51
	v_rcp_f32_e32 v51, v51
	s_nop 0
	v_mul_f32_e32 v53, v51, v50
	v_cvt_pk_bf16_f32 v50, v0, v54
	v_cvt_pk_bf16_f32 v51, v55, v56
	v_cvt_pk_bf16_f32 v52, v57, v58
	v_cvt_pk_bf16_f32 v53, v59, v53
	global_store_dwordx4 v[62:63], v[50:53], off offset:256
	s_nop 1
	v_mov_b32_e32 v50, v230
	v_mov_b32_e32 v51, v231
	v_mov_b32_e32 v52, v232
	v_mov_b32_e32 v53, v233
	v_mov_b32_e32 v54, v226
	v_mov_b32_e32 v55, v227
	v_mov_b32_e32 v56, v228
	v_mov_b32_e32 v57, v229
	v_lshlrev_b32_e32 v0, 16, v86
	v_add_f32_e32 v42, v42, v50
	v_add_f32_e32 v46, v46, v54
	v_mul_f32_e32 v46, 0xbfb8aa3b, v46
	v_add_f32_e32 v47, v47, v55
	v_exp_f32_e32 v46, v46
	v_mul_f32_e32 v47, 0xbfb8aa3b, v47
	v_add_f32_e32 v48, v48, v56
	v_exp_f32_e32 v47, v47
	v_mul_f32_e32 v48, 0xbfb8aa3b, v48
	v_add_f32_e32 v49, v49, v57
	v_exp_f32_e32 v48, v48
	v_mul_f32_e32 v49, 0xbfb8aa3b, v49
	v_exp_f32_e32 v49, v49
	v_mul_f32_e32 v42, 0xbfb8aa3b, v42
	v_add_f32_e32 v43, v43, v51
	v_add_f32_e32 v46, 1.0, v46
	v_exp_f32_e32 v42, v42
	v_mul_f32_e32 v43, 0xbfb8aa3b, v43
	v_rcp_f32_e32 v46, v46
	v_add_f32_e32 v47, 1.0, v47
	v_exp_f32_e32 v43, v43
	v_rcp_f32_e32 v47, v47
	v_add_f32_e32 v48, 1.0, v48
	v_rcp_f32_e32 v48, v48
	v_add_f32_e32 v49, 1.0, v49
	v_rcp_f32_e32 v49, v49
	v_add_f32_e32 v42, 1.0, v42
	v_mul_f32_e32 v0, v46, v0
	v_and_b32_e32 v46, 0xffff0000, v86
	v_rcp_f32_e32 v42, v42
	v_add_f32_e32 v43, 1.0, v43
	v_mul_f32_e32 v46, v47, v46
	v_lshlrev_b32_e32 v47, 16, v87
	v_rcp_f32_e32 v43, v43
	v_mul_f32_e32 v47, v48, v47
	v_and_b32_e32 v48, 0xffff0000, v87
	v_mul_f32_e32 v48, v49, v48
	v_lshlrev_b32_e32 v49, 16, v88
	v_mul_f32_e32 v49, v42, v49
	v_and_b32_e32 v42, 0xffff0000, v88
	v_mul_f32_e32 v50, v43, v42
	v_add_f32_e32 v43, v44, v52
	v_mul_f32_e32 v43, 0xbfb8aa3b, v43
	v_exp_f32_e32 v43, v43
	v_lshlrev_b32_e32 v42, 16, v89
	v_add_f32_e32 v43, 1.0, v43
	v_rcp_f32_e32 v43, v43
	s_nop 0
	v_mul_f32_e32 v51, v43, v42
	v_add_f32_e32 v43, v45, v53
	v_mul_f32_e32 v43, 0xbfb8aa3b, v43
	v_exp_f32_e32 v43, v43
	v_and_b32_e32 v42, 0xffff0000, v89
	v_add_f32_e32 v43, 1.0, v43
	v_rcp_f32_e32 v43, v43
	s_nop 0
	v_mul_f32_e32 v45, v43, v42
	v_cvt_pk_bf16_f32 v42, v0, v46
	v_cvt_pk_bf16_f32 v43, v47, v48
	v_add_co_u32_e32 v48, vcc, s1, v146
	v_cvt_pk_bf16_f32 v44, v49, v50
	v_cvt_pk_bf16_f32 v45, v51, v45
	v_lshlrev_b32_e32 v0, 16, v82
	s_nop 0
	v_addc_co_u32_e32 v49, vcc, 0, v147, vcc
	global_store_dwordx4 v[48:49], v[42:45], off
	s_nop 1
	v_mov_b32_e32 v42, v204
	v_mov_b32_e32 v43, v205
	v_mov_b32_e32 v44, v206
	v_mov_b32_e32 v45, v207
	v_mov_b32_e32 v48, v234
	v_mov_b32_e32 v49, v235
	v_mov_b32_e32 v50, v236
	v_mov_b32_e32 v51, v237
	v_lshl_add_u64 v[46:47], v[146:147], 0, s[28:29]
	s_mov_b32 s1, 0x50000
	s_mov_b64 s[28:29], 0x50000
	v_add_f32_e32 v34, v34, v42
	v_add_f32_e32 v38, v38, v48
	v_mul_f32_e32 v38, 0xbfb8aa3b, v38
	v_add_f32_e32 v39, v39, v49
	v_exp_f32_e32 v38, v38
	v_mul_f32_e32 v39, 0xbfb8aa3b, v39
	v_add_f32_e32 v40, v40, v50
	v_exp_f32_e32 v39, v39
	v_mul_f32_e32 v40, 0xbfb8aa3b, v40
	v_add_f32_e32 v41, v41, v51
	v_exp_f32_e32 v40, v40
	v_mul_f32_e32 v41, 0xbfb8aa3b, v41
	v_exp_f32_e32 v41, v41
	v_mul_f32_e32 v34, 0xbfb8aa3b, v34
	v_add_f32_e32 v35, v35, v43
	v_add_f32_e32 v38, 1.0, v38
	v_exp_f32_e32 v34, v34
	v_mul_f32_e32 v35, 0xbfb8aa3b, v35
	v_rcp_f32_e32 v38, v38
	v_add_f32_e32 v39, 1.0, v39
	v_exp_f32_e32 v35, v35
	v_rcp_f32_e32 v39, v39
	v_add_f32_e32 v40, 1.0, v40
	v_rcp_f32_e32 v40, v40
	v_add_f32_e32 v41, 1.0, v41
	v_rcp_f32_e32 v41, v41
	v_add_f32_e32 v34, 1.0, v34
	v_mul_f32_e32 v0, v38, v0
	v_and_b32_e32 v38, 0xffff0000, v82
	v_rcp_f32_e32 v34, v34
	v_add_f32_e32 v35, 1.0, v35
	v_mul_f32_e32 v38, v39, v38
	v_lshlrev_b32_e32 v39, 16, v83
	v_rcp_f32_e32 v35, v35
; __device__ __forceinline__ unsigned cvt_pk_bf16(float lo, float hi) { unsigned r; asm volatile("v_cvt_pk_bf16_f32 %0, %1, %2" : "=v"(r) : "v"(lo), "v"(hi)); return r; }
; __device__ __forceinline__ float fast_sigmoid(float x) { return __builtin_amdgcn_rcpf(1.0f + __expf(-x)); }
;     __device__ __forceinline__ void operator()(const f32x4 (&acc)[2][2][4][2], const Unit& u, int wr, int wc, int fr, int fq, PG8_LAS unsigned char* ldsb) const {
;     ...
;             for (int m = 0; m < 4; ++m) {
;                 const int row = row0 + ai * HALF + m * 16;
; #pragma unroll
;                 for (int bj = 0; bj < 2; ++bj) {
;                     const int c = col0 + bj * HALF;
;                     const u32x4 zw = zv[m][bj];
;                     float v[8];
; #pragma unroll
;                     for (int n = 0; n < 2; ++n)
; #pragma unroll
;                         for (int i = 0; i < 4; ++i) { const int e = n * 4 + i; const unsigned wd = zw[e >> 1];
;                             const float z = __uint_as_float((e & 1) ? (wd & 0xffff0000u) : (wd << 16));
;                             v[e] = z * fast_sigmoid(acc[ai][bj][m][n][i] + bias[c + e]); }
;                     u32x4 w; w.x = cvt_pk_bf16(v[0], v[1]); w.y = cvt_pk_bf16(v[2], v[3]); w.z = cvt_pk_bf16(v[4], v[5]); w.w = cvt_pk_bf16(v[6], v[7]);
;                     *(u32x4*)(O + (size_t)row * ldo + c) = w;
;                 }
;             }
	v_mul_f32_e32 v39, v40, v39
	v_and_b32_e32 v40, 0xffff0000, v83
	v_mul_f32_e32 v40, v41, v40
	v_lshlrev_b32_e32 v41, 16, v84
	v_mul_f32_e32 v41, v34, v41
	v_and_b32_e32 v34, 0xffff0000, v84
	v_mul_f32_e32 v42, v35, v34
	v_add_f32_e32 v35, v36, v44
	v_mul_f32_e32 v35, 0xbfb8aa3b, v35
	v_exp_f32_e32 v35, v35
	v_lshlrev_b32_e32 v34, 16, v85
	v_add_f32_e32 v35, 1.0, v35
	v_rcp_f32_e32 v35, v35
	s_nop 0
	v_mul_f32_e32 v43, v35, v34
	v_add_f32_e32 v35, v37, v45
	v_mul_f32_e32 v35, 0xbfb8aa3b, v35
	v_exp_f32_e32 v35, v35
	v_and_b32_e32 v34, 0xffff0000, v85
	v_add_f32_e32 v35, 1.0, v35
	v_rcp_f32_e32 v35, v35
	s_nop 0
	v_mul_f32_e32 v37, v35, v34
	v_cvt_pk_bf16_f32 v34, v0, v38
	v_cvt_pk_bf16_f32 v35, v39, v40
	v_cvt_pk_bf16_f32 v36, v41, v42
	v_cvt_pk_bf16_f32 v37, v43, v37
	global_store_dwordx4 v[46:47], v[34:37], off offset:256
	s_nop 1
	v_mov_b32_e32 v34, v230
	v_mov_b32_e32 v35, v231
	v_mov_b32_e32 v36, v232
	v_mov_b32_e32 v37, v233
	v_mov_b32_e32 v38, v226
	v_mov_b32_e32 v39, v227
	v_mov_b32_e32 v40, v228
	v_mov_b32_e32 v41, v229
	v_lshlrev_b32_e32 v0, 16, v78
	v_add_f32_e32 v26, v26, v34
	v_add_f32_e32 v30, v30, v38
	v_mul_f32_e32 v30, 0xbfb8aa3b, v30
	v_add_f32_e32 v31, v31, v39
	v_exp_f32_e32 v30, v30
	v_mul_f32_e32 v31, 0xbfb8aa3b, v31
	v_add_f32_e32 v32, v32, v40
	v_exp_f32_e32 v31, v31
	v_mul_f32_e32 v32, 0xbfb8aa3b, v32
	v_add_f32_e32 v33, v33, v41
	v_exp_f32_e32 v32, v32
	v_mul_f32_e32 v33, 0xbfb8aa3b, v33
	v_exp_f32_e32 v33, v33
	v_mul_f32_e32 v26, 0xbfb8aa3b, v26
	v_add_f32_e32 v27, v27, v35
	v_add_f32_e32 v30, 1.0, v30
	v_exp_f32_e32 v26, v26
	v_mul_f32_e32 v27, 0xbfb8aa3b, v27
	v_rcp_f32_e32 v30, v30
	v_add_f32_e32 v31, 1.0, v31
	v_exp_f32_e32 v27, v27
	v_rcp_f32_e32 v31, v31
	v_add_f32_e32 v32, 1.0, v32
	v_rcp_f32_e32 v32, v32
	v_add_f32_e32 v33, 1.0, v33
	v_rcp_f32_e32 v33, v33
	v_add_f32_e32 v26, 1.0, v26
	v_mul_f32_e32 v0, v30, v0
	v_and_b32_e32 v30, 0xffff0000, v78
	v_rcp_f32_e32 v26, v26
	v_add_f32_e32 v27, 1.0, v27
	v_mul_f32_e32 v30, v31, v30
	v_lshlrev_b32_e32 v31, 16, v79
	v_rcp_f32_e32 v27, v27
	v_mul_f32_e32 v31, v32, v31
	v_and_b32_e32 v32, 0xffff0000, v79
	v_mul_f32_e32 v32, v33, v32
	v_lshlrev_b32_e32 v33, 16, v80
	v_mul_f32_e32 v33, v26, v33
	v_and_b32_e32 v26, 0xffff0000, v80
	v_mul_f32_e32 v34, v27, v26
	v_add_f32_e32 v27, v28, v36
	v_mul_f32_e32 v27, 0xbfb8aa3b, v27
	v_exp_f32_e32 v27, v27
	v_lshlrev_b32_e32 v26, 16, v81
	v_add_f32_e32 v27, 1.0, v27
	v_rcp_f32_e32 v27, v27
	s_nop 0
	v_mul_f32_e32 v35, v27, v26
	v_add_f32_e32 v27, v29, v37
	v_mul_f32_e32 v27, 0xbfb8aa3b, v27
	v_exp_f32_e32 v27, v27
	v_and_b32_e32 v26, 0xffff0000, v81
	v_add_f32_e32 v27, 1.0, v27
	v_rcp_f32_e32 v27, v27
	s_nop 0
	v_mul_f32_e32 v29, v27, v26
	v_cvt_pk_bf16_f32 v26, v0, v30
	v_cvt_pk_bf16_f32 v27, v31, v32
	v_add_co_u32_e32 v32, vcc, s1, v146
	v_cvt_pk_bf16_f32 v28, v33, v34
	v_cvt_pk_bf16_f32 v29, v35, v29
	v_lshlrev_b32_e32 v0, 16, v74
	s_nop 0
	v_addc_co_u32_e32 v33, vcc, 0, v147, vcc
	global_store_dwordx4 v[32:33], v[26:29], off
	s_nop 1
	v_mov_b32_e32 v26, v204
	v_mov_b32_e32 v27, v205
	v_mov_b32_e32 v28, v206
	v_mov_b32_e32 v29, v207
	v_mov_b32_e32 v32, v234
	v_mov_b32_e32 v33, v235
	v_mov_b32_e32 v34, v236
	v_mov_b32_e32 v35, v237
	v_lshl_add_u64 v[30:31], v[146:147], 0, s[28:29]
	s_mov_b32 s1, 0x58000
	s_mov_b64 s[28:29], 0x58000
	v_add_f32_e32 v18, v18, v26
	v_add_f32_e32 v22, v22, v32
	v_mul_f32_e32 v22, 0xbfb8aa3b, v22
	v_add_f32_e32 v23, v23, v33
	v_exp_f32_e32 v22, v22
	v_mul_f32_e32 v23, 0xbfb8aa3b, v23
	v_add_f32_e32 v24, v24, v34
	v_exp_f32_e32 v23, v23
	v_mul_f32_e32 v24, 0xbfb8aa3b, v24
	v_add_f32_e32 v25, v25, v35
	v_exp_f32_e32 v24, v24
	v_mul_f32_e32 v25, 0xbfb8aa3b, v25
	v_exp_f32_e32 v25, v25
	v_mul_f32_e32 v18, 0xbfb8aa3b, v18
	v_add_f32_e32 v19, v19, v27
	v_add_f32_e32 v22, 1.0, v22
	v_exp_f32_e32 v18, v18
	v_mul_f32_e32 v19, 0xbfb8aa3b, v19
	v_rcp_f32_e32 v22, v22
	v_add_f32_e32 v23, 1.0, v23
	v_exp_f32_e32 v19, v19
	v_rcp_f32_e32 v23, v23
	v_add_f32_e32 v24, 1.0, v24
	v_rcp_f32_e32 v24, v24
	v_add_f32_e32 v25, 1.0, v25
	v_rcp_f32_e32 v25, v25
	v_add_f32_e32 v18, 1.0, v18
	v_mul_f32_e32 v0, v22, v0
	v_and_b32_e32 v22, 0xffff0000, v74
	v_rcp_f32_e32 v18, v18
	v_add_f32_e32 v19, 1.0, v19
	v_mul_f32_e32 v22, v23, v22
	v_lshlrev_b32_e32 v23, 16, v75
	v_rcp_f32_e32 v19, v19
	v_mul_f32_e32 v23, v24, v23
	v_and_b32_e32 v24, 0xffff0000, v75
	v_mul_f32_e32 v24, v25, v24
	v_lshlrev_b32_e32 v25, 16, v76
	v_mul_f32_e32 v25, v18, v25
	v_and_b32_e32 v18, 0xffff0000, v76
	v_mul_f32_e32 v26, v19, v18
	v_add_f32_e32 v19, v20, v28
	v_mul_f32_e32 v19, 0xbfb8aa3b, v19
	v_exp_f32_e32 v19, v19
	v_lshlrev_b32_e32 v18, 16, v77
	v_add_f32_e32 v19, 1.0, v19
	v_rcp_f32_e32 v19, v19
	s_nop 0
	v_mul_f32_e32 v27, v19, v18
; __device__ __forceinline__ unsigned cvt_pk_bf16(float lo, float hi) { unsigned r; asm volatile("v_cvt_pk_bf16_f32 %0, %1, %2" : "=v"(r) : "v"(lo), "v"(hi)); return r; }
; __device__ __forceinline__ float fast_sigmoid(float x) { return __builtin_amdgcn_rcpf(1.0f + __expf(-x)); }
; #define PG8_BAR __builtin_amdgcn_s_barrier()
;     __device__ __forceinline__ void operator()(const f32x4 (&acc)[2][2][4][2], const Unit& u, int wr, int wc, int fr, int fq, PG8_LAS unsigned char* ldsb) const {
;     ...
;             for (int m = 0; m < 4; ++m) {
;                 const int row = row0 + ai * HALF + m * 16;
; #pragma unroll
;                 for (int bj = 0; bj < 2; ++bj) {
;                     const int c = col0 + bj * HALF;
;                     const u32x4 zw = zv[m][bj];
;                     float v[8];
; #pragma unroll
;                     for (int n = 0; n < 2; ++n)
; #pragma unroll
;                         for (int i = 0; i < 4; ++i) { const int e = n * 4 + i; const unsigned wd = zw[e >> 1];
;                             const float z = __uint_as_float((e & 1) ? (wd & 0xffff0000u) : (wd << 16));
;                             v[e] = z * fast_sigmoid(acc[ai][bj][m][n][i] + bias[c + e]); }
;                     u32x4 w; w.x = cvt_pk_bf16(v[0], v[1]); w.y = cvt_pk_bf16(v[2], v[3]); w.z = cvt_pk_bf16(v[4], v[5]); w.w = cvt_pk_bf16(v[6], v[7]);
;                     *(u32x4*)(O + (size_t)row * ldo + c) = w;
;                 }
;             }
; template <class Epi, class Sched, bool ALIGN_EPI = false, bool SP2 = false>
; __device__ __forceinline__ void gemm_phase(PG8_LAS unsigned char* lds, const Gemm g, const Sched& S, const Epi& E) {
;     ...
;         if constexpr (ALIGN_EPI) { if (wr == 0) PG8_BAR; }
;         if constexpr (!Epi::AFTER_DRAIN) { E(acc, cur, wr, wc, fr, fq, lds); S.done(cur); }
;         if (!has_next) break;
; #pragma unroll
;         for (int a = 0; a < 2; ++a)
; #pragma unroll
;             for (int b = 0; b < 2; ++b)
; #pragma unroll
;                 for (int m = 0; m < 4; ++m)
; #pragma unroll
;                     for (int n = 0; n < 2; ++n) acc[a][b][m][n] = (f32x4){0.f, 0.f, 0.f, 0.f};
;         cur = nxt; cA = nA; cB = nB; ++ui;
;         if constexpr (ALIGN_EPI) { if (wr == 1) PG8_BAR; }
	v_add_f32_e32 v19, v21, v29
	v_mul_f32_e32 v19, 0xbfb8aa3b, v19
	v_exp_f32_e32 v19, v19
	v_and_b32_e32 v18, 0xffff0000, v77
	v_add_f32_e32 v19, 1.0, v19
	v_rcp_f32_e32 v19, v19
	s_nop 0
	v_mul_f32_e32 v21, v19, v18
	v_cvt_pk_bf16_f32 v18, v0, v22
	v_cvt_pk_bf16_f32 v19, v23, v24
	v_cvt_pk_bf16_f32 v20, v25, v26
	v_cvt_pk_bf16_f32 v21, v27, v21
	global_store_dwordx4 v[30:31], v[18:21], off offset:256
	s_nop 1
	v_mov_b32_e32 v18, v230
	v_mov_b32_e32 v19, v231
	v_mov_b32_e32 v20, v232
	v_mov_b32_e32 v21, v233
	v_mov_b32_e32 v22, v226
	v_mov_b32_e32 v23, v227
	v_mov_b32_e32 v24, v228
	v_mov_b32_e32 v25, v229
	v_lshlrev_b32_e32 v0, 16, v70
	v_add_f32_e32 v10, v10, v18
	v_add_f32_e32 v14, v14, v22
	v_mul_f32_e32 v14, 0xbfb8aa3b, v14
	v_add_f32_e32 v15, v15, v23
	v_exp_f32_e32 v14, v14
	v_mul_f32_e32 v15, 0xbfb8aa3b, v15
	v_add_f32_e32 v16, v16, v24
	v_exp_f32_e32 v15, v15
	v_mul_f32_e32 v16, 0xbfb8aa3b, v16
	v_add_f32_e32 v17, v17, v25
	v_exp_f32_e32 v16, v16
	v_mul_f32_e32 v17, 0xbfb8aa3b, v17
	v_exp_f32_e32 v17, v17
	v_mul_f32_e32 v10, 0xbfb8aa3b, v10
	v_add_f32_e32 v11, v11, v19
	v_add_f32_e32 v14, 1.0, v14
	v_exp_f32_e32 v10, v10
	v_mul_f32_e32 v11, 0xbfb8aa3b, v11
	v_rcp_f32_e32 v14, v14
	v_add_f32_e32 v15, 1.0, v15
	v_exp_f32_e32 v11, v11
	v_rcp_f32_e32 v15, v15
	v_add_f32_e32 v16, 1.0, v16
	v_rcp_f32_e32 v16, v16
	v_add_f32_e32 v17, 1.0, v17
	v_rcp_f32_e32 v17, v17
	v_add_f32_e32 v10, 1.0, v10
	v_mul_f32_e32 v0, v14, v0
	v_and_b32_e32 v14, 0xffff0000, v70
	v_rcp_f32_e32 v10, v10
	v_add_f32_e32 v11, 1.0, v11
	v_mul_f32_e32 v14, v15, v14
	v_lshlrev_b32_e32 v15, 16, v71
	v_rcp_f32_e32 v11, v11
	v_mul_f32_e32 v15, v16, v15
	v_and_b32_e32 v16, 0xffff0000, v71
	v_mul_f32_e32 v16, v17, v16
	v_lshlrev_b32_e32 v17, 16, v72
	v_mul_f32_e32 v17, v10, v17
	v_and_b32_e32 v10, 0xffff0000, v72
	v_mul_f32_e32 v18, v11, v10
	v_add_f32_e32 v11, v12, v20
	v_mul_f32_e32 v11, 0xbfb8aa3b, v11
	v_exp_f32_e32 v11, v11
	v_lshlrev_b32_e32 v10, 16, v73
	v_add_f32_e32 v11, 1.0, v11
	v_rcp_f32_e32 v11, v11
	s_nop 0
	v_mul_f32_e32 v19, v11, v10
	v_add_f32_e32 v11, v13, v21
	v_mul_f32_e32 v11, 0xbfb8aa3b, v11
	v_exp_f32_e32 v11, v11
	v_and_b32_e32 v10, 0xffff0000, v73
	v_add_f32_e32 v11, 1.0, v11
	v_rcp_f32_e32 v11, v11
	s_nop 0
	v_mul_f32_e32 v13, v11, v10
	v_cvt_pk_bf16_f32 v10, v0, v14
	v_cvt_pk_bf16_f32 v11, v15, v16
	v_add_co_u32_e32 v16, vcc, s1, v146
	v_cvt_pk_bf16_f32 v12, v17, v18
	v_cvt_pk_bf16_f32 v13, v19, v13
	v_lshlrev_b32_e32 v0, 16, v66
	s_nop 0
	v_addc_co_u32_e32 v17, vcc, 0, v147, vcc
	global_store_dwordx4 v[16:17], v[10:13], off
	s_nop 1
	v_mov_b32_e32 v10, v204
	v_mov_b32_e32 v11, v205
	v_mov_b32_e32 v12, v206
	v_mov_b32_e32 v13, v207
	v_mov_b32_e32 v16, v234
	v_mov_b32_e32 v17, v235
	v_mov_b32_e32 v18, v236
	v_mov_b32_e32 v19, v237
	v_lshl_add_u64 v[14:15], v[146:147], 0, s[28:29]
	s_mov_b64 s[28:29], -1
	s_and_b64 vcc, exec, s[2:3]
	v_add_f32_e32 v2, v2, v10
	v_add_f32_e32 v6, v6, v16
	v_mul_f32_e32 v6, 0xbfb8aa3b, v6
	v_add_f32_e32 v7, v7, v17
	v_exp_f32_e32 v6, v6
	v_mul_f32_e32 v7, 0xbfb8aa3b, v7
	v_add_f32_e32 v8, v8, v18
	v_exp_f32_e32 v7, v7
	v_mul_f32_e32 v8, 0xbfb8aa3b, v8
	v_add_f32_e32 v9, v9, v19
	v_exp_f32_e32 v8, v8
	v_mul_f32_e32 v9, 0xbfb8aa3b, v9
	v_exp_f32_e32 v9, v9
	v_mul_f32_e32 v2, 0xbfb8aa3b, v2
	v_add_f32_e32 v3, v3, v11
	v_add_f32_e32 v6, 1.0, v6
	v_exp_f32_e32 v2, v2
	v_mul_f32_e32 v3, 0xbfb8aa3b, v3
	v_rcp_f32_e32 v6, v6
	v_add_f32_e32 v7, 1.0, v7
	v_exp_f32_e32 v3, v3
	v_rcp_f32_e32 v7, v7
	v_add_f32_e32 v8, 1.0, v8
	v_rcp_f32_e32 v8, v8
	v_add_f32_e32 v9, 1.0, v9
	v_rcp_f32_e32 v9, v9
	v_add_f32_e32 v2, 1.0, v2
	v_mul_f32_e32 v0, v6, v0
	v_and_b32_e32 v6, 0xffff0000, v66
	v_rcp_f32_e32 v2, v2
	v_add_f32_e32 v3, 1.0, v3
	v_mul_f32_e32 v6, v7, v6
	v_lshlrev_b32_e32 v7, 16, v67
	v_rcp_f32_e32 v3, v3
	v_mul_f32_e32 v7, v8, v7
	v_and_b32_e32 v8, 0xffff0000, v67
	v_mul_f32_e32 v8, v9, v8
	v_lshlrev_b32_e32 v9, 16, v68
	v_mul_f32_e32 v9, v2, v9
	v_and_b32_e32 v2, 0xffff0000, v68
	v_mul_f32_e32 v10, v3, v2
	v_add_f32_e32 v3, v4, v12
	v_mul_f32_e32 v3, 0xbfb8aa3b, v3
	v_exp_f32_e32 v3, v3
	v_lshlrev_b32_e32 v2, 16, v69
	v_add_f32_e32 v3, 1.0, v3
	v_rcp_f32_e32 v3, v3
	s_nop 0
	v_mul_f32_e32 v11, v3, v2
	v_add_f32_e32 v3, v5, v13
	v_mul_f32_e32 v3, 0xbfb8aa3b, v3
	v_exp_f32_e32 v3, v3
	v_and_b32_e32 v2, 0xffff0000, v69
	v_add_f32_e32 v3, 1.0, v3
	v_rcp_f32_e32 v3, v3
	s_nop 0
	v_mul_f32_e32 v5, v3, v2
	v_cvt_pk_bf16_f32 v2, v0, v6
	v_cvt_pk_bf16_f32 v3, v7, v8
	v_cvt_pk_bf16_f32 v4, v9, v10
	v_cvt_pk_bf16_f32 v5, v11, v5
	global_store_dwordx4 v[14:15], v[2:5], off offset:256
	s_cbranch_vccnz .LBB0_808
	s_andn2_b64 vcc, exec, s[16:17]
	s_cbranch_vccnz .LBB0_807
	s_barrier
	s_branch .LBB0_807
